# up-projection epilogue: conv weight/bias loads issued in front of the halo barrier instead of after it
# baseline (speedup 1.0000x reference)
; #define PG8_LAS __attribute__((address_space(3)))
; __device__ __forceinline__ float dpp_ror1(float v) { return __int_as_float(__builtin_amdgcn_update_dpp(0, __float_as_int(v), 0x121, 0xf, 0xf, false)); }
; __device__ __forceinline__ float dpp_ror2(float v) { return __int_as_float(__builtin_amdgcn_update_dpp(0, __float_as_int(v), 0x122, 0xf, 0xf, false)); }
;     __device__ __forceinline__ void operator()(const f32x4 (&acc)[2][2][4][2], const Unit& u, int wr, int wc, int fr, int fq) const {
;     ...
;             for (int m = 0; m < 4; ++m) rn[ai][m] = row_rstd(rss, (long)b * 4096 + 254 * i - 2 + ai * HALF + wr * 64 + m * 16 + fr, fq);
;         if (fr >= 14) {
; #pragma unroll
;             for (int ai = 0; ai < 2; ++ai)
; #pragma unroll
;                 for (int n = 0; n < 2; ++n) *(PG8_LAS f32x4*)(halo + ((ai * 2 + wr) * 2 + (fr - 14)) * 128 + fl + 4 * n) = acc[ai][0][3][n] * rn[ai][3];
;         }
;         asm volatile("s_waitcnt lgkmcnt(0)" ::: "memory"); __builtin_amdgcn_s_barrier(); asm volatile("" ::: "memory");
;         f32x4 w0[2], w1[2], w2[2], bb[2];
; #pragma unroll
;         for (int n = 0; n < 2; ++n) { w0[n] = *(const f32x4*)(cw + f0 + 4 * n); w1[n] = *(const f32x4*)(cw + 2816 + f0 + 4 * n); w2[n] = *(const f32x4*)(cw + 2 * 2816 + f0 + 4 * n); bb[n] = *(const f32x4*)(cb + f0 + 4 * n); }
; #pragma unroll
;         for (int ai = 0; ai < 2; ++ai) {
;             const int blk = ai * 2 + wr;
;             f32x4 pc1[2], pc2[2];
; #pragma unroll
;             for (int n = 0; n < 2; ++n) { f32x4 hv = {0.f, 0.f, 0.f, 0.f};
;                 if (blk > 0 && fr >= 14) hv = *(const PG8_LAS f32x4*)(halo + ((blk - 1) * 2 + (fr - 14)) * 128 + fl + 4 * n);
; #pragma unroll
;                 for (int j = 0; j < 4; ++j) { pc1[n][j] = dpp_ror1(hv[j]); pc2[n][j] = dpp_ror2(hv[j]); } }
.LBB0_293:
	s_or_b64 exec, exec, s[6:7]
	v_lshl_or_b32 v182, s8, 7, v173
	v_ashrrev_i32_e32 v183, 31, v182
	v_lshlrev_b64 v[64:65], 2, v[182:183]
	s_waitcnt lgkmcnt(0)
	v_lshl_add_u64 v[66:67], s[20:21], 0, v[64:65]
	v_lshl_add_u64 v[68:69], s[66:67], 0, v[64:65]
	v_lshl_add_u64 v[76:77], s[68:69], 0, v[64:65]
	v_lshl_add_u64 v[100:101], s[26:27], 0, v[64:65]
	global_load_dwordx4 v[72:75], v[66:67], off offset:16
	global_load_dwordx4 v[96:99], v[66:67], off
	s_nop 0
	global_load_dwordx4 v[64:67], v[68:69], off offset:16
	global_load_dwordx4 v[88:91], v[68:69], off
	s_nop 0
	global_load_dwordx4 v[68:71], v[76:77], off offset:16
	global_load_dwordx4 v[92:95], v[76:77], off
	s_nop 0
	global_load_dwordx4 v[76:79], v[100:101], off offset:16
	s_nop 0
	global_load_dwordx4 v[100:103], v[100:101], off
	s_barrier
	v_mov_b32_e32 v160, 0
	v_mov_b32_e32 v162, 0
	v_mov_b32_e32 v163, 0
	v_mov_b32_e32 v164, 0
	v_mov_b32_e32 v165, 0
	s_and_saveexec_b64 s[6:7], s[60:61]
	ds_read_b128 v[162:165], v206
	s_or_b64 exec, exec, s[6:7]
	s_waitcnt lgkmcnt(0)
	v_mov_b32_dpp v228, v162 row_ror:1 row_mask:0xf bank_mask:0xf
	v_mov_b32_dpp v230, v162 row_ror:2 row_mask:0xf bank_mask:0xf
	v_mov_b32_dpp v229, v163 row_ror:1 row_mask:0xf bank_mask:0xf
	v_mov_b32_dpp v231, v163 row_ror:2 row_mask:0xf bank_mask:0xf
	v_mov_b32_dpp v236, v164 row_ror:1 row_mask:0xf bank_mask:0xf
	v_mov_b32_dpp v238, v164 row_ror:2 row_mask:0xf bank_mask:0xf
	v_mov_b32_dpp v237, v165 row_ror:1 row_mask:0xf bank_mask:0xf
	v_mov_b32_dpp v239, v165 row_ror:2 row_mask:0xf bank_mask:0xf
	v_mov_b32_e32 v161, 0
	v_mov_b32_e32 v162, 0
	v_mov_b32_e32 v163, 0
	s_and_saveexec_b64 s[6:7], s[60:61]
	ds_read_b128 v[160:163], v206 offset:16
	s_or_b64 exec, exec, s[6:7]
	v_pk_add_f32 v[164:165], v[192:193], v[194:195]
	s_add_i32 s77, s77, -2
	v_pk_fma_f32 v[164:165], v[164:165], s[78:79], v[210:211] op_sel_hi:[1,0,0]
	v_add_u32_e32 v227, s77, v172
	v_mul_f32_e32 v192, 0x4b800000, v165
	v_cmp_gt_f32_e64 s[8:9], s39, v165
	s_nop 1
	v_cndmask_b32_e64 v165, v165, v192, s[8:9]
	v_rsq_f32_e32 v165, v165
	s_waitcnt lgkmcnt(0)
	v_mov_b32_dpp v240, v160 row_ror:1 row_mask:0xf bank_mask:0xf
	v_mul_f32_e32 v192, 0x45800000, v165
	v_cndmask_b32_e64 v192, v165, v192, s[8:9]
	v_pk_mul_f32 v[156:157], v[156:157], v[192:193] op_sel_hi:[1,0]
	v_cmp_gt_i32_e64 s[8:9], 0, v227
	v_pk_mul_f32 v[158:159], v[158:159], v[192:193] op_sel_hi:[1,0]
	s_nop 0
	v_cndmask_b32_e64 v157, v157, 0, s[8:9]
	v_mov_b32_dpp v242, v160 row_ror:2 row_mask:0xf bank_mask:0xf
	v_mov_b32_dpp v241, v161 row_ror:1 row_mask:0xf bank_mask:0xf
	v_mov_b32_dpp v193, v157 row_ror:1 row_mask:0xf bank_mask:0xf
	v_mov_b32_dpp v243, v161 row_ror:2 row_mask:0xf bank_mask:0xf
	v_pk_mul_f32 v[160:161], v[152:153], v[192:193] op_sel_hi:[1,0]
	v_pk_mul_f32 v[152:153], v[154:155], v[192:193] op_sel_hi:[1,0]
	v_mov_b32_dpp v232, v162 row_ror:1 row_mask:0xf bank_mask:0xf
	v_mov_b32_dpp v234, v162 row_ror:2 row_mask:0xf bank_mask:0xf
	v_mov_b32_dpp v233, v163 row_ror:1 row_mask:0xf bank_mask:0xf
	v_mov_b32_dpp v235, v163 row_ror:2 row_mask:0xf bank_mask:0xf
	v_cndmask_b32_e64 v159, v159, 0, s[8:9]
	v_cndmask_b32_e64 v158, v158, 0, s[8:9]
	v_cndmask_b32_e64 v156, v156, 0, s[8:9]
	v_cndmask_b32_e64 v153, v153, 0, s[8:9]
	v_cndmask_b32_e64 v152, v152, 0, s[8:9]
	v_cndmask_b32_e64 v155, v161, 0, s[8:9]
	v_cndmask_b32_e64 v154, v160, 0, s[8:9]
	v_cmp_gt_i32_e64 s[8:9], s83, v227
	s_lshl_b32 s71, s76, 12
	v_cmp_gt_f32_e64 s[6:7], s39, v164
	v_mov_b32_dpp v165, v156 row_ror:1 row_mask:0xf bank_mask:0xf
	v_mov_b32_dpp v194, v156 row_ror:2 row_mask:0xf bank_mask:0xf
	v_mov_b32_dpp v195, v157 row_ror:2 row_mask:0xf bank_mask:0xf
	v_mov_b32_dpp v219, v158 row_ror:1 row_mask:0xf bank_mask:0xf
	v_mov_b32_dpp v221, v158 row_ror:2 row_mask:0xf bank_mask:0xf
	v_mov_b32_dpp v220, v159 row_ror:1 row_mask:0xf bank_mask:0xf
	v_mov_b32_dpp v222, v159 row_ror:2 row_mask:0xf bank_mask:0xf
	v_mov_b32_dpp v223, v154 row_ror:1 row_mask:0xf bank_mask:0xf
	v_mov_b32_dpp v225, v154 row_ror:2 row_mask:0xf bank_mask:0xf
	v_mov_b32_dpp v224, v155 row_ror:1 row_mask:0xf bank_mask:0xf
	v_mov_b32_dpp v226, v155 row_ror:2 row_mask:0xf bank_mask:0xf
	v_mov_b32_dpp v160, v152 row_ror:1 row_mask:0xf bank_mask:0xf
	v_mov_b32_dpp v162, v152 row_ror:2 row_mask:0xf bank_mask:0xf
	v_mov_b32_dpp v161, v153 row_ror:1 row_mask:0xf bank_mask:0xf
	v_mov_b32_dpp v163, v153 row_ror:2 row_mask:0xf bank_mask:0xf
	s_and_b64 s[18:19], s[46:47], s[8:9]
	s_waitcnt vmcnt(0)
	s_and_saveexec_b64 s[8:9], s[18:19]
	s_cbranch_execz .LBB0_299
; __device__ __forceinline__ u32x4 pack8(const f32x4& v0, const f32x4& v1) { u32x4 w; w.x = cvt_pk_bf16(v0[0], v0[1]); w.y = cvt_pk_bf16(v0[2], v0[3]); w.z = cvt_pk_bf16(v1[0], v1[1]); w.w = cvt_pk_bf16(v1[2], v1[3]); return w; }
; __device__ __forceinline__ float dpp_ror1(float v) { return __int_as_float(__builtin_amdgcn_update_dpp(0, __float_as_int(v), 0x121, 0xf, 0xf, false)); }
; __device__ __forceinline__ float dpp_ror2(float v) { return __int_as_float(__builtin_amdgcn_update_dpp(0, __float_as_int(v), 0x122, 0xf, 0xf, false)); }
;     __device__ __forceinline__ void operator()(const f32x4 (&acc)[2][2][4][2], const Unit& u, int wr, int wc, int fr, int fq) const {
;     ...
;             for (int m = 0; m < 4; ++m) { const int r = ai * HALF + wr * 64 + m * 16 + fr, tk = 254 * i - 2 + r;
;                 f32x4 o[2];
; #pragma unroll
;                 for (int n = 0; n < 2; ++n) { f32x4 cur = acc[ai][0][m][n] * rn[ai][m]; if (tk < 0) cur = (f32x4){0.f, 0.f, 0.f, 0.f};
; #pragma unroll
;                     for (int j = 0; j < 4; ++j) { const float c1 = dpp_ror1(cur[j]), c2 = dpp_ror2(cur[j]);
;                         const float p1 = fr >= 1 ? c1 : pc1[n][j], p2 = fr >= 2 ? c2 : pc2[n][j]; pc1[n][j] = c1; pc2[n][j] = c2;
;                         const float cv = bb[n][j] + w0[n][j] * p2 + w1[n][j] * p1 + w2[n][j] * cur[j];
;                         o[n][j] = gelu_t(cv) * (acc[ai][1][m][n][j] * rn[ai][m]); } }
;                 if (r >= 2 && tk < 4096) *(u32x4*)(ACT + (size_t)(b * 4096 + tk) * 2816 + f0) = pack8(o[0], o[1]); }
	v_cndmask_b32_e64 v213, v243, v226, s[44:45]
	v_cndmask_b32_e64 v212, v242, v225, s[44:45]
	v_pk_fma_f32 v[212:213], v[72:73], v[212:213], v[76:77]
	v_cndmask_b32_e64 v215, v224, v241, s[42:43]
	v_cndmask_b32_e64 v214, v223, v240, s[42:43]
	v_pk_fma_f32 v[212:213], v[64:65], v[214:215], v[212:213]
	v_pk_mul_f32 v[144:145], v[144:145], v[192:193] op_sel_hi:[1,0]
	v_pk_fma_f32 v[154:155], v[154:155], v[68:69], v[212:213]
	v_pk_mul_f32 v[150:151], v[150:151], v[192:193] op_sel_hi:[1,0]
	v_mul_f32_e32 v212, 0x3d122279, v154
	v_mul_f32_e32 v213, 0x3d122279, v155
	v_fmaak_f32 v212, v154, v212, 0x3f4c422a
	v_fmaak_f32 v213, v155, v213, 0x3f4c422a
	v_mul_f32_e32 v212, v154, v212
	v_mul_f32_e32 v213, v155, v213
	v_mul_f32_e32 v212, 0xc038aa3b, v212
	v_mul_f32_e32 v213, 0xc038aa3b, v213
	v_exp_f32_e32 v212, v212
	v_exp_f32_e32 v213, v213
	v_pk_mul_f32 v[148:149], v[148:149], v[192:193] op_sel_hi:[1,0]
	v_pk_mul_f32 v[146:147], v[146:147], v[192:193] op_sel_hi:[1,0]
	v_add_f32_e32 v212, 1.0, v212
	v_add_f32_e32 v213, 1.0, v213
	v_rcp_f32_e32 v212, v212
	v_rcp_f32_e32 v213, v213
	s_nop 0
	v_pk_mul_f32 v[154:155], v[154:155], v[212:213]
	s_nop 0
	v_pk_mul_f32 v[154:155], v[144:145], v[154:155]
	v_cndmask_b32_e64 v145, v239, v222, s[44:45]
	v_cndmask_b32_e64 v144, v238, v221, s[44:45]
	v_pk_fma_f32 v[144:145], v[98:99], v[144:145], v[102:103]
	v_cndmask_b32_e64 v213, v220, v237, s[42:43]
	v_cndmask_b32_e64 v212, v219, v236, s[42:43]
	v_pk_fma_f32 v[144:145], v[90:91], v[212:213], v[144:145]
	s_nop 0
	v_pk_fma_f32 v[144:145], v[158:159], v[94:95], v[144:145]
	s_nop 0
	v_mul_f32_e32 v158, 0x3d122279, v144
	v_mul_f32_e32 v159, 0x3d122279, v145
	v_fmaak_f32 v158, v144, v158, 0x3f4c422a
	v_fmaak_f32 v159, v145, v159, 0x3f4c422a
	v_mul_f32_e32 v158, v144, v158
	v_mul_f32_e32 v159, v145, v159
	v_mul_f32_e32 v158, 0xc038aa3b, v158
	v_mul_f32_e32 v159, 0xc038aa3b, v159
	v_exp_f32_e32 v158, v158
	v_exp_f32_e32 v159, v159
	v_add_f32_e32 v158, 1.0, v158
	v_add_f32_e32 v159, 1.0, v159
	v_rcp_f32_e32 v158, v158
	v_rcp_f32_e32 v159, v159
	s_nop 0
	v_pk_mul_f32 v[144:145], v[144:145], v[158:159]
	s_nop 0
	v_pk_mul_f32 v[150:151], v[150:151], v[144:145]
	v_cndmask_b32_e64 v145, v231, v195, s[44:45]
	v_cndmask_b32_e64 v144, v230, v194, s[44:45]
	v_pk_fma_f32 v[144:145], v[96:97], v[144:145], v[100:101]
	v_cndmask_b32_e64 v159, v193, v229, s[42:43]
	v_cndmask_b32_e64 v158, v165, v228, s[42:43]
	v_pk_fma_f32 v[144:145], v[88:89], v[158:159], v[144:145]
	s_nop 0
	v_pk_fma_f32 v[144:145], v[156:157], v[92:93], v[144:145]
	s_nop 0
	v_mul_f32_e32 v156, 0x3d122279, v144
	v_mul_f32_e32 v157, 0x3d122279, v145
	v_fmaak_f32 v156, v144, v156, 0x3f4c422a
	v_fmaak_f32 v157, v145, v157, 0x3f4c422a
	v_mul_f32_e32 v156, v144, v156
	v_mul_f32_e32 v157, v145, v157
	v_mul_f32_e32 v156, 0xc038aa3b, v156
	v_mul_f32_e32 v157, 0xc038aa3b, v157
	v_exp_f32_e32 v156, v156
	v_exp_f32_e32 v157, v157
	v_add_f32_e32 v156, 1.0, v156
	v_add_f32_e32 v157, 1.0, v157
	v_rcp_f32_e32 v156, v156
	v_rcp_f32_e32 v157, v157
	s_nop 0
	v_pk_mul_f32 v[144:145], v[144:145], v[156:157]
	s_nop 0
	v_pk_mul_f32 v[144:145], v[148:149], v[144:145]
	v_cndmask_b32_e64 v149, v235, v163, s[44:45]
	v_cndmask_b32_e64 v148, v234, v162, s[44:45]
	v_cndmask_b32_e64 v157, v161, v233, s[42:43]
	v_cndmask_b32_e64 v156, v160, v232, s[42:43]
	v_pk_fma_f32 v[148:149], v[74:75], v[148:149], v[78:79]
	v_cvt_pk_bf16_f32 v144, v144, v145
	v_pk_fma_f32 v[148:149], v[66:67], v[156:157], v[148:149]
	v_cvt_pk_bf16_f32 v145, v150, v151
	v_pk_fma_f32 v[148:149], v[152:153], v[70:71], v[148:149]
	v_add_u32_e32 v150, s71, v227
	v_mul_f32_e32 v152, 0x3d122279, v148
	v_mul_f32_e32 v153, 0x3d122279, v149
	v_fmaak_f32 v152, v148, v152, 0x3f4c422a
	v_fmaak_f32 v153, v149, v153, 0x3f4c422a
	v_mul_f32_e32 v152, v148, v152
	v_mul_f32_e32 v153, v149, v153
	v_mul_f32_e32 v152, 0xc038aa3b, v152
	v_mul_f32_e32 v153, 0xc038aa3b, v153
	v_exp_f32_e32 v152, v152
	v_exp_f32_e32 v153, v153
	v_add_f32_e32 v152, 1.0, v152
	v_add_f32_e32 v153, 1.0, v153
	v_rcp_f32_e32 v152, v152
	v_rcp_f32_e32 v153, v153
	s_nop 0
	v_pk_mul_f32 v[148:149], v[148:149], v[152:153]
	s_nop 0
	v_pk_mul_f32 v[148:149], v[146:147], v[148:149]
	v_cvt_pk_bf16_f32 v146, v154, v155
	v_cvt_pk_bf16_f32 v147, v148, v149
	v_mov_b64_e32 v[148:149], s[12:13]
	v_mad_i64_i32 v[148:149], s[18:19], v150, s34, v[148:149]
	v_lshl_add_u64 v[148:149], v[182:183], 1, v[148:149]
	global_store_dwordx4 v[148:149], v[144:147], off
